# M3 norm/gate/store epilogue: 16 gate + norm-weight loads per query block issued together instead of store->load->wait per group
# speedup vs baseline: 1.0037x; 1.0037x over previous
.LBB0_876:
	v_add_f32_e32 v32, 0x358637bd, v35
	v_cmp_gt_f32_e32 vcc, s73, v32
	v_mul_f32_e32 v33, 0x4f800000, v32
	v_ashrrev_i32_e32 v113, 31, v112
	v_cndmask_b32_e32 v32, v32, v33, vcc
	v_sqrt_f32_e32 v33, v32
	s_add_i32 s2, s2, s72
	s_cmpk_gt_i32 s2, 0xff
	s_waitcnt lgkmcnt(0)
	v_add_u32_e32 v34, -1, v33
	v_fma_f32 v35, -v34, v33, v32
	v_cmp_ge_f32_e64 s[38:39], 0, v35
	v_add_u32_e32 v35, 1, v33
	s_nop 0
	v_cndmask_b32_e64 v34, v33, v34, s[38:39]
	v_fma_f32 v33, -v35, v33, v32
	v_cmp_lt_f32_e64 s[38:39], 0, v33
	s_nop 1
	v_cndmask_b32_e64 v33, v34, v35, s[38:39]
	v_mul_f32_e32 v34, 0x37800000, v33
	v_cndmask_b32_e32 v33, v33, v34, vcc
	v_cmp_class_f32_e32 vcc, v32, v236
	s_nop 1
	v_cndmask_b32_e32 v32, v33, v32, vcc
	v_div_scale_f32 v33, s[4:5], v32, v32, 1.0
	v_rcp_f32_e32 v34, v33
	s_nop 0
	v_fma_f32 v35, -v33, v34, 1.0
	v_fmac_f32_e32 v34, v35, v34
	v_div_scale_f32 v35, vcc, 1.0, v32, 1.0
	v_mul_f32_e32 v37, v35, v34
	v_fma_f32 v38, -v33, v37, v35
	v_fmac_f32_e32 v37, v38, v34
	v_fma_f32 v33, -v33, v37, v35
	v_div_fmas_f32 v33, v33, v34, v37
	v_div_fixup_f32 v38, v33, v32, 1.0
	v_mov_b64_e32 v[32:33], s[34:35]
	v_mad_i64_i32 v[32:33], s[4:5], v112, s84, v[32:33]
	v_lshlrev_b64 v[34:35], 11, v[112:113]
	v_lshl_add_u64 v[32:33], v[192:193], 1, v[32:33]
	v_lshl_add_u64 v[34:35], s[20:21], 0, v[34:35]
	v_lshl_add_u64 v[34:35], s[42:43], 1, v[34:35]
	v_lshl_add_u64 v[40:41], v[32:33], 0, v[70:71]
	v_lshl_add_u64 v[42:43], s[26:27], 1, v[34:35]
	global_load_dwordx2 v[44:45], v[40:41], off
	global_load_dwordx4 v[32:35], v[68:69], off
	global_load_dwordx2 v[156:157], v[40:41], off offset:16
	global_load_dwordx2 v[158:159], v[40:41], off offset:32
	global_load_dwordx2 v[160:161], v[40:41], off offset:48
	global_load_dwordx2 v[162:163], v[40:41], off offset:64
	global_load_dwordx2 v[164:165], v[40:41], off offset:80
	global_load_dwordx2 v[166:167], v[40:41], off offset:96
	global_load_dwordx2 v[168:169], v[40:41], off offset:112
	global_load_dwordx4 v[172:175], v[68:69], off offset:32
	global_load_dwordx4 v[176:179], v[68:69], off offset:64
	global_load_dwordx4 v[180:183], v[68:69], off offset:96
	global_load_dwordx4 v[184:187], v[68:69], off offset:128
	global_load_dwordx4 v[188:191], v[68:69], off offset:160
	global_load_dwordx4 v[206:209], v[68:69], off offset:192
	global_load_dwordx4 v[210:213], v[68:69], off offset:224
	v_pk_add_f32 v[16:17], v[16:17], v[36:37] op_sel_hi:[1,0] neg_lo:[0,1] neg_hi:[0,1]
	s_waitcnt vmcnt(15)
	v_and_b32_e32 v39, 0xffff0000, v44
	v_lshlrev_b32_e32 v37, 16, v44
	v_pk_mul_f32 v[16:17], v[16:17], v[38:39] op_sel_hi:[1,0]
	v_mul_f32_e32 v44, 0xbfb8aa3b, v37
	s_waitcnt vmcnt(14)
	v_pk_mul_f32 v[16:17], v[32:33], v[16:17]
	v_mul_f32_e32 v32, 0xbfb8aa3b, v39
	v_exp_f32_e32 v46, v44
	v_exp_f32_e32 v47, v32
	v_pk_add_f32 v[18:19], v[18:19], v[36:37] op_sel_hi:[1,0] neg_lo:[0,1] neg_hi:[0,1]
	v_pk_add_f32 v[32:33], v[46:47], 1.0 op_sel_hi:[1,0]
	s_nop 0
	v_div_scale_f32 v44, s[4:5], v33, v33, v39
	v_rcp_f32_e32 v46, v44
	s_nop 0
	v_fma_f32 v47, -v44, v46, 1.0
	v_fmac_f32_e32 v46, v47, v46
	v_div_scale_f32 v47, vcc, v39, v33, v39
	v_mul_f32_e32 v48, v47, v46
	v_fma_f32 v49, -v44, v48, v47
	v_fmac_f32_e32 v48, v49, v46
	v_fma_f32 v44, -v44, v48, v47
	v_div_fmas_f32 v44, v44, v46, v48
	v_div_fixup_f32 v33, v44, v33, v39
	v_div_scale_f32 v39, s[4:5], v32, v32, v37
	v_rcp_f32_e32 v44, v39
	s_nop 0
	v_fma_f32 v46, -v39, v44, 1.0
	v_fmac_f32_e32 v44, v46, v44
	v_div_scale_f32 v46, vcc, v37, v32, v37
	v_mul_f32_e32 v47, v46, v44
	v_fma_f32 v48, -v39, v47, v46
	v_fmac_f32_e32 v47, v48, v44
	v_fma_f32 v39, -v39, v47, v46
	v_div_fmas_f32 v39, v39, v44, v47
	v_div_fixup_f32 v32, v39, v32, v37
	v_lshlrev_b32_e32 v37, 16, v45
	v_and_b32_e32 v39, 0xffff0000, v45
	v_pk_mul_f32 v[16:17], v[16:17], v[32:33]
	v_mul_f32_e32 v32, 0xbfb8aa3b, v37
	v_mul_f32_e32 v33, 0xbfb8aa3b, v39
	v_exp_f32_e32 v32, v32
	v_exp_f32_e32 v33, v33
	v_pk_mul_f32 v[18:19], v[18:19], v[38:39] op_sel_hi:[1,0]
	v_pk_add_f32 v[32:33], v[32:33], 1.0 op_sel_hi:[1,0]
	v_pk_mul_f32 v[18:19], v[34:35], v[18:19]
	v_div_scale_f32 v34, s[4:5], v33, v33, v39
	v_rcp_f32_e32 v35, v34
	s_nop 0
	v_fma_f32 v44, -v34, v35, 1.0
	v_fmac_f32_e32 v35, v44, v35
	v_div_scale_f32 v44, vcc, v39, v33, v39
	v_mul_f32_e32 v45, v44, v35
	v_fma_f32 v46, -v34, v45, v44
	v_fmac_f32_e32 v45, v46, v35
	v_fma_f32 v34, -v34, v45, v44
	v_div_fmas_f32 v34, v34, v35, v45
	v_div_fixup_f32 v33, v34, v33, v39
	v_div_scale_f32 v34, s[4:5], v32, v32, v37
	v_rcp_f32_e32 v35, v34
	s_nop 0
	v_fma_f32 v39, -v34, v35, 1.0
	v_fmac_f32_e32 v35, v39, v35
	v_div_scale_f32 v39, vcc, v37, v32, v37
	v_mul_f32_e32 v44, v39, v35
	v_fma_f32 v45, -v34, v44, v39
	v_fmac_f32_e32 v44, v45, v35
	v_fma_f32 v34, -v34, v44, v39
	v_div_fmas_f32 v34, v34, v35, v44
	v_div_fixup_f32 v32, v34, v32, v37
	v_pk_mul_f32 v[18:19], v[18:19], v[32:33]
	v_cvt_pk_bf16_f32 v32, v16, v17
	v_cvt_pk_bf16_f32 v33, v18, v19
	v_lshl_add_u64 v[16:17], v[42:43], 0, v[70:71]
	global_store_dwordx2 v[16:17], v[32:33], off
	s_waitcnt vmcnt(1)
	v_mov_b64_e32 v[42:43], v[156:157]
	v_mov_b64_e32 v[32:33], v[172:173]
	v_mov_b64_e32 v[34:35], v[174:175]
	v_pk_add_f32 v[18:19], v[20:21], v[36:37] op_sel_hi:[1,0] neg_lo:[0,1] neg_hi:[0,1]
	v_lshlrev_b32_e32 v37, 16, v42
	v_and_b32_e32 v39, 0xffff0000, v42
	v_mul_f32_e32 v20, 0xbfb8aa3b, v37
	v_mul_f32_e32 v21, 0xbfb8aa3b, v39
	v_exp_f32_e32 v20, v20
	v_exp_f32_e32 v21, v21
	v_pk_mul_f32 v[18:19], v[18:19], v[38:39] op_sel_hi:[1,0]
	v_pk_add_f32 v[20:21], v[20:21], 1.0 op_sel_hi:[1,0]
	v_pk_mul_f32 v[18:19], v[18:19], v[32:33]
	v_div_scale_f32 v32, s[4:5], v21, v21, v39
	v_rcp_f32_e32 v33, v32
	s_nop 0
	v_fma_f32 v42, -v32, v33, 1.0
	v_fmac_f32_e32 v33, v42, v33
	v_div_scale_f32 v42, vcc, v39, v21, v39
	v_mul_f32_e32 v44, v42, v33
	v_fma_f32 v45, -v32, v44, v42
	v_fmac_f32_e32 v44, v45, v33
	v_fma_f32 v32, -v32, v44, v42
	v_div_fmas_f32 v32, v32, v33, v44
	v_div_fixup_f32 v21, v32, v21, v39
	v_div_scale_f32 v32, s[4:5], v20, v20, v37
	v_rcp_f32_e32 v33, v32
	s_nop 0
	v_fma_f32 v39, -v32, v33, 1.0
	v_fmac_f32_e32 v33, v39, v33
	v_div_scale_f32 v39, vcc, v37, v20, v37
	v_mul_f32_e32 v42, v39, v33
	v_fma_f32 v44, -v32, v42, v39
	v_fmac_f32_e32 v42, v44, v33
	v_fma_f32 v32, -v32, v42, v39
	v_div_fmas_f32 v32, v32, v33, v42
	v_div_fixup_f32 v20, v32, v20, v37
	v_lshlrev_b32_e32 v32, 16, v43
	v_and_b32_e32 v33, 0xffff0000, v43
	v_pk_mul_f32 v[18:19], v[18:19], v[20:21]
	v_pk_add_f32 v[20:21], v[22:23], v[36:37] op_sel_hi:[1,0] neg_lo:[0,1] neg_hi:[0,1]
	v_mul_f32_e32 v22, 0xbfb8aa3b, v32
	v_mul_f32_e32 v23, 0xbfb8aa3b, v33
	v_exp_f32_e32 v22, v22
	v_exp_f32_e32 v23, v23
	v_pk_mul_f32 v[20:21], v[20:21], v[38:39] op_sel_hi:[1,0]
	v_cvt_pk_bf16_f32 v18, v18, v19
	v_pk_mul_f32 v[20:21], v[20:21], v[34:35]
	v_pk_add_f32 v[22:23], v[22:23], 1.0 op_sel_hi:[1,0]
	s_nop 0
	v_div_scale_f32 v34, s[4:5], v23, v23, v33
	v_rcp_f32_e32 v35, v34
	s_nop 0
	v_fma_f32 v37, -v34, v35, 1.0
	v_fmac_f32_e32 v35, v37, v35
	v_div_scale_f32 v37, vcc, v33, v23, v33
	v_mul_f32_e32 v39, v37, v35
	v_fma_f32 v42, -v34, v39, v37
	v_fmac_f32_e32 v39, v42, v35
	v_fma_f32 v34, -v34, v39, v37
	v_div_fmas_f32 v34, v34, v35, v39
	v_div_fixup_f32 v23, v34, v23, v33
	v_div_scale_f32 v33, s[4:5], v22, v22, v32
	v_rcp_f32_e32 v34, v33
	s_nop 0
	v_fma_f32 v35, -v33, v34, 1.0
	v_fmac_f32_e32 v34, v35, v34
	v_div_scale_f32 v35, vcc, v32, v22, v32
	v_mul_f32_e32 v37, v35, v34
	v_fma_f32 v39, -v33, v37, v35
	v_fmac_f32_e32 v37, v39, v34
	v_fma_f32 v33, -v33, v37, v35
	v_div_fmas_f32 v33, v33, v34, v37
	v_div_fixup_f32 v22, v33, v22, v32
	v_pk_mul_f32 v[20:21], v[20:21], v[22:23]
	v_pk_add_f32 v[24:25], v[24:25], v[36:37] op_sel_hi:[1,0] neg_lo:[0,1] neg_hi:[0,1]
	v_cvt_pk_bf16_f32 v19, v20, v21
	global_store_dwordx2 v[16:17], v[18:19], off offset:16
	s_waitcnt vmcnt(2)
	v_mov_b64_e32 v[22:23], v[158:159]
	v_mov_b64_e32 v[18:19], v[176:177]
	v_mov_b64_e32 v[20:21], v[178:179]
	v_pk_mul_f32 v[24:25], v[24:25], v[38:39] op_sel_hi:[1,0]
	v_lshlrev_b32_e32 v34, 16, v22
	v_and_b32_e32 v22, 0xffff0000, v22
	v_mul_f32_e32 v32, 0xbfb8aa3b, v34
	v_pk_mul_f32 v[18:19], v[24:25], v[18:19]
	v_mul_f32_e32 v24, 0xbfb8aa3b, v22
	v_exp_f32_e32 v32, v32
	v_exp_f32_e32 v33, v24
	s_nop 0
	v_pk_add_f32 v[24:25], v[32:33], 1.0 op_sel_hi:[1,0]
	s_nop 0
	v_div_scale_f32 v32, s[4:5], v25, v25, v22
	v_rcp_f32_e32 v33, v32
	s_nop 0
	v_fma_f32 v35, -v32, v33, 1.0
	v_fmac_f32_e32 v33, v35, v33
	v_div_scale_f32 v35, vcc, v22, v25, v22
	v_mul_f32_e32 v37, v35, v33
	v_fma_f32 v39, -v32, v37, v35
	v_fmac_f32_e32 v37, v39, v33
	v_fma_f32 v32, -v32, v37, v35
	v_div_fmas_f32 v32, v32, v33, v37
	v_div_fixup_f32 v25, v32, v25, v22
	v_div_scale_f32 v22, s[4:5], v24, v24, v34
	v_rcp_f32_e32 v32, v22
	s_nop 0
	v_fma_f32 v33, -v22, v32, 1.0
	v_fmac_f32_e32 v32, v33, v32
	v_div_scale_f32 v33, vcc, v34, v24, v34
	v_mul_f32_e32 v35, v33, v32
	v_fma_f32 v37, -v22, v35, v33
	v_fmac_f32_e32 v35, v37, v32
	v_fma_f32 v22, -v22, v35, v33
	v_div_fmas_f32 v22, v22, v32, v35
	v_div_fixup_f32 v24, v22, v24, v34
	v_pk_mul_f32 v[18:19], v[18:19], v[24:25]
	v_pk_add_f32 v[24:25], v[26:27], v[36:37] op_sel_hi:[1,0] neg_lo:[0,1] neg_hi:[0,1]
	v_lshlrev_b32_e32 v26, 16, v23
	v_and_b32_e32 v27, 0xffff0000, v23
	v_mul_f32_e32 v22, 0xbfb8aa3b, v26
	v_mul_f32_e32 v23, 0xbfb8aa3b, v27
	v_exp_f32_e32 v22, v22
	v_exp_f32_e32 v23, v23
	v_pk_mul_f32 v[24:25], v[24:25], v[38:39] op_sel_hi:[1,0]
	v_cvt_pk_bf16_f32 v18, v18, v19
	v_pk_mul_f32 v[20:21], v[24:25], v[20:21]
	v_pk_add_f32 v[22:23], v[22:23], 1.0 op_sel_hi:[1,0]
	v_pk_add_f32 v[0:1], v[0:1], v[36:37] op_sel_hi:[1,0] neg_lo:[0,1] neg_hi:[0,1]
	v_div_scale_f32 v24, s[4:5], v23, v23, v27
	v_rcp_f32_e32 v25, v24
	v_pk_mul_f32 v[0:1], v[0:1], v[38:39] op_sel_hi:[1,0]
	v_pk_add_f32 v[2:3], v[2:3], v[36:37] op_sel_hi:[1,0] neg_lo:[0,1] neg_hi:[0,1]
	v_pk_add_f32 v[4:5], v[4:5], v[36:37] op_sel_hi:[1,0] neg_lo:[0,1] neg_hi:[0,1]
	v_fma_f32 v32, -v24, v25, 1.0
	v_fmac_f32_e32 v25, v32, v25
	v_div_scale_f32 v32, vcc, v27, v23, v27
	v_mul_f32_e32 v33, v32, v25
	v_fma_f32 v34, -v24, v33, v32
	v_fmac_f32_e32 v33, v34, v25
	v_fma_f32 v24, -v24, v33, v32
	v_div_fmas_f32 v24, v24, v25, v33
	v_div_fixup_f32 v23, v24, v23, v27
	v_div_scale_f32 v24, s[4:5], v22, v22, v26
	v_rcp_f32_e32 v25, v24
	v_pk_mul_f32 v[2:3], v[2:3], v[38:39] op_sel_hi:[1,0]
	v_pk_mul_f32 v[4:5], v[4:5], v[38:39] op_sel_hi:[1,0]
	v_fma_f32 v27, -v24, v25, 1.0
	v_fmac_f32_e32 v25, v27, v25
	v_div_scale_f32 v27, vcc, v26, v22, v26
	v_mul_f32_e32 v32, v27, v25
	v_fma_f32 v33, -v24, v32, v27
	v_fmac_f32_e32 v32, v33, v25
	v_fma_f32 v24, -v24, v32, v27
	v_div_fmas_f32 v24, v24, v25, v32
	v_div_fixup_f32 v22, v24, v22, v26
	v_pk_mul_f32 v[20:21], v[20:21], v[22:23]
	v_pk_add_f32 v[24:25], v[28:29], v[36:37] op_sel_hi:[1,0] neg_lo:[0,1] neg_hi:[0,1]
	v_cvt_pk_bf16_f32 v19, v20, v21
	global_store_dwordx2 v[16:17], v[18:19], off offset:32
	s_waitcnt vmcnt(3)
	v_mov_b64_e32 v[22:23], v[160:161]
	v_mov_b64_e32 v[18:19], v[180:181]
	v_mov_b64_e32 v[20:21], v[182:183]
	v_pk_mul_f32 v[24:25], v[24:25], v[38:39] op_sel_hi:[1,0]
	v_lshlrev_b32_e32 v28, 16, v22
	v_and_b32_e32 v22, 0xffff0000, v22
	v_mul_f32_e32 v26, 0xbfb8aa3b, v28
	v_pk_mul_f32 v[18:19], v[24:25], v[18:19]
	v_mul_f32_e32 v24, 0xbfb8aa3b, v22
	v_exp_f32_e32 v26, v26
	v_exp_f32_e32 v27, v24
	s_nop 0
	v_pk_add_f32 v[24:25], v[26:27], 1.0 op_sel_hi:[1,0]
	s_nop 0
	v_div_scale_f32 v26, s[4:5], v25, v25, v22
	v_rcp_f32_e32 v27, v26
	s_nop 0
	v_fma_f32 v29, -v26, v27, 1.0
	v_fmac_f32_e32 v27, v29, v27
	v_div_scale_f32 v29, vcc, v22, v25, v22
	v_mul_f32_e32 v32, v29, v27
	v_fma_f32 v33, -v26, v32, v29
	v_fmac_f32_e32 v32, v33, v27
	v_fma_f32 v26, -v26, v32, v29
	v_div_fmas_f32 v26, v26, v27, v32
	v_div_fixup_f32 v25, v26, v25, v22
	v_div_scale_f32 v22, s[4:5], v24, v24, v28
	v_rcp_f32_e32 v26, v22
	s_nop 0
	v_fma_f32 v27, -v22, v26, 1.0
	v_fmac_f32_e32 v26, v27, v26
	v_div_scale_f32 v27, vcc, v28, v24, v28
	v_mul_f32_e32 v29, v27, v26
	v_fma_f32 v32, -v22, v29, v27
	v_fmac_f32_e32 v29, v32, v26
	v_fma_f32 v22, -v22, v29, v27
	v_div_fmas_f32 v22, v22, v26, v29
	v_lshlrev_b32_e32 v26, 16, v23
	v_and_b32_e32 v27, 0xffff0000, v23
	v_div_fixup_f32 v24, v22, v24, v28
	v_mul_f32_e32 v22, 0xbfb8aa3b, v26
	v_mul_f32_e32 v23, 0xbfb8aa3b, v27
	v_exp_f32_e32 v22, v22
	v_exp_f32_e32 v23, v23
	v_pk_mul_f32 v[18:19], v[18:19], v[24:25]
	v_pk_add_f32 v[24:25], v[30:31], v[36:37] op_sel_hi:[1,0] neg_lo:[0,1] neg_hi:[0,1]
	v_cvt_pk_bf16_f32 v18, v18, v19
	v_pk_mul_f32 v[24:25], v[24:25], v[38:39] op_sel_hi:[1,0]
	v_pk_add_f32 v[22:23], v[22:23], 1.0 op_sel_hi:[1,0]
	v_pk_mul_f32 v[20:21], v[24:25], v[20:21]
	v_div_scale_f32 v24, s[4:5], v23, v23, v27
	v_rcp_f32_e32 v25, v24
	s_nop 0
	v_fma_f32 v28, -v24, v25, 1.0
	v_fmac_f32_e32 v25, v28, v25
	v_div_scale_f32 v28, vcc, v27, v23, v27
	v_mul_f32_e32 v29, v28, v25
	v_fma_f32 v30, -v24, v29, v28
	v_fmac_f32_e32 v29, v30, v25
	v_fma_f32 v24, -v24, v29, v28
	v_div_fmas_f32 v24, v24, v25, v29
	v_div_fixup_f32 v23, v24, v23, v27
	v_div_scale_f32 v24, s[4:5], v22, v22, v26
	v_rcp_f32_e32 v25, v24
	s_nop 0
	v_fma_f32 v27, -v24, v25, 1.0
	v_fmac_f32_e32 v25, v27, v25
	v_div_scale_f32 v27, vcc, v26, v22, v26
	v_mul_f32_e32 v28, v27, v25
	v_fma_f32 v29, -v24, v28, v27
	v_fmac_f32_e32 v28, v29, v25
	v_fma_f32 v24, -v24, v28, v27
	v_div_fmas_f32 v24, v24, v25, v28
	v_div_fixup_f32 v22, v24, v22, v26
	v_pk_mul_f32 v[20:21], v[20:21], v[22:23]
	s_nop 0
	v_cvt_pk_bf16_f32 v19, v20, v21
	global_store_dwordx2 v[16:17], v[18:19], off offset:48
	s_waitcnt vmcnt(4)
	v_mov_b64_e32 v[22:23], v[162:163]
	v_mov_b64_e32 v[18:19], v[184:185]
	v_mov_b64_e32 v[20:21], v[186:187]
	v_lshlrev_b32_e32 v26, 16, v22
	v_and_b32_e32 v22, 0xffff0000, v22
	v_mul_f32_e32 v24, 0xbfb8aa3b, v26
	v_pk_mul_f32 v[0:1], v[0:1], v[18:19]
	v_mul_f32_e32 v18, 0xbfb8aa3b, v22
	v_exp_f32_e32 v24, v24
	v_exp_f32_e32 v25, v18
	v_pk_mul_f32 v[2:3], v[2:3], v[20:21]
	v_pk_add_f32 v[18:19], v[24:25], 1.0 op_sel_hi:[1,0]
	s_nop 0
	v_div_scale_f32 v24, s[4:5], v19, v19, v22
	v_rcp_f32_e32 v25, v24
	s_nop 0
	v_fma_f32 v27, -v24, v25, 1.0
	v_fmac_f32_e32 v25, v27, v25
	v_div_scale_f32 v27, vcc, v22, v19, v22
	v_mul_f32_e32 v28, v27, v25
	v_fma_f32 v29, -v24, v28, v27
	v_fmac_f32_e32 v28, v29, v25
	v_fma_f32 v24, -v24, v28, v27
	v_div_fmas_f32 v24, v24, v25, v28
	v_div_fixup_f32 v19, v24, v19, v22
	v_div_scale_f32 v22, s[4:5], v18, v18, v26
	v_rcp_f32_e32 v24, v22
	s_nop 0
	v_fma_f32 v25, -v22, v24, 1.0
	v_fmac_f32_e32 v24, v25, v24
	v_div_scale_f32 v25, vcc, v26, v18, v26
	v_mul_f32_e32 v27, v25, v24
	v_fma_f32 v28, -v22, v27, v25
	v_fmac_f32_e32 v27, v28, v24
	v_fma_f32 v22, -v22, v27, v25
	v_div_fmas_f32 v22, v22, v24, v27
	v_div_fixup_f32 v18, v22, v18, v26
	v_lshlrev_b32_e32 v22, 16, v23
	v_and_b32_e32 v23, 0xffff0000, v23
	v_pk_mul_f32 v[0:1], v[0:1], v[18:19]
	v_mul_f32_e32 v18, 0xbfb8aa3b, v22
	v_mul_f32_e32 v19, 0xbfb8aa3b, v23
	v_exp_f32_e32 v18, v18
	v_exp_f32_e32 v19, v19
	v_cvt_pk_bf16_f32 v0, v0, v1
	v_pk_add_f32 v[18:19], v[18:19], 1.0 op_sel_hi:[1,0]
	s_nop 0
	v_div_scale_f32 v20, s[4:5], v19, v19, v23
	v_rcp_f32_e32 v21, v20
	s_nop 0
	v_fma_f32 v24, -v20, v21, 1.0
	v_fmac_f32_e32 v21, v24, v21
	v_div_scale_f32 v24, vcc, v23, v19, v23
	v_mul_f32_e32 v25, v24, v21
	v_fma_f32 v26, -v20, v25, v24
	v_fmac_f32_e32 v25, v26, v21
	v_fma_f32 v20, -v20, v25, v24
	v_div_fmas_f32 v20, v20, v21, v25
	v_div_fixup_f32 v19, v20, v19, v23
	v_div_scale_f32 v20, s[4:5], v18, v18, v22
	v_rcp_f32_e32 v21, v20
	s_nop 0
	v_fma_f32 v23, -v20, v21, 1.0
	v_fmac_f32_e32 v21, v23, v21
	v_div_scale_f32 v23, vcc, v22, v18, v22
	v_mul_f32_e32 v24, v23, v21
	v_fma_f32 v25, -v20, v24, v23
	v_fmac_f32_e32 v24, v25, v21
	v_fma_f32 v20, -v20, v24, v23
	v_div_fmas_f32 v20, v20, v21, v24
	v_div_fixup_f32 v18, v20, v18, v22
	v_pk_mul_f32 v[2:3], v[2:3], v[18:19]
	s_nop 0
	v_cvt_pk_bf16_f32 v1, v2, v3
	global_store_dwordx2 v[16:17], v[0:1], off offset:64
	s_waitcnt vmcnt(5)
	v_mov_b64_e32 v[18:19], v[164:165]
	v_mov_b64_e32 v[0:1], v[188:189]
	v_mov_b64_e32 v[2:3], v[190:191]
	v_lshlrev_b32_e32 v22, 16, v18
	v_and_b32_e32 v18, 0xffff0000, v18
	v_mul_f32_e32 v20, 0xbfb8aa3b, v22
	v_pk_mul_f32 v[0:1], v[4:5], v[0:1]
	v_mul_f32_e32 v4, 0xbfb8aa3b, v18
	v_exp_f32_e32 v20, v20
	v_exp_f32_e32 v21, v4
	s_nop 0
	v_pk_add_f32 v[4:5], v[20:21], 1.0 op_sel_hi:[1,0]
	s_nop 0
	v_div_scale_f32 v20, s[4:5], v5, v5, v18
	v_rcp_f32_e32 v21, v20
	s_nop 0
	v_fma_f32 v23, -v20, v21, 1.0
	v_fmac_f32_e32 v21, v23, v21
	v_div_scale_f32 v23, vcc, v18, v5, v18
	v_mul_f32_e32 v24, v23, v21
	v_fma_f32 v25, -v20, v24, v23
	v_fmac_f32_e32 v24, v25, v21
	v_fma_f32 v20, -v20, v24, v23
	v_div_fmas_f32 v20, v20, v21, v24
	v_div_fixup_f32 v5, v20, v5, v18
	v_div_scale_f32 v18, s[4:5], v4, v4, v22
	v_rcp_f32_e32 v20, v18
	s_nop 0
	v_fma_f32 v21, -v18, v20, 1.0
	v_fmac_f32_e32 v20, v21, v20
	v_div_scale_f32 v21, vcc, v22, v4, v22
	v_mul_f32_e32 v23, v21, v20
	v_fma_f32 v24, -v18, v23, v21
	v_fmac_f32_e32 v23, v24, v20
	v_fma_f32 v18, -v18, v23, v21
	v_div_fmas_f32 v18, v18, v20, v23
	v_div_fixup_f32 v4, v18, v4, v22
	v_pk_mul_f32 v[0:1], v[0:1], v[4:5]
	v_pk_add_f32 v[4:5], v[6:7], v[36:37] op_sel_hi:[1,0] neg_lo:[0,1] neg_hi:[0,1]
	v_lshlrev_b32_e32 v18, 16, v19
	v_and_b32_e32 v19, 0xffff0000, v19
	v_pk_mul_f32 v[4:5], v[4:5], v[38:39] op_sel_hi:[1,0]
	v_mul_f32_e32 v6, 0xbfb8aa3b, v18
	v_pk_mul_f32 v[2:3], v[4:5], v[2:3]
	v_mul_f32_e32 v4, 0xbfb8aa3b, v19
	v_exp_f32_e32 v6, v6
	v_exp_f32_e32 v7, v4
	v_cvt_pk_bf16_f32 v0, v0, v1
	v_pk_add_f32 v[4:5], v[6:7], 1.0 op_sel_hi:[1,0]
	s_nop 0
	v_div_scale_f32 v6, s[4:5], v5, v5, v19
	v_rcp_f32_e32 v7, v6
	s_nop 0
	v_fma_f32 v20, -v6, v7, 1.0
	v_fmac_f32_e32 v7, v20, v7
	v_div_scale_f32 v20, vcc, v19, v5, v19
	v_mul_f32_e32 v21, v20, v7
	v_fma_f32 v22, -v6, v21, v20
	v_fmac_f32_e32 v21, v22, v7
	v_fma_f32 v6, -v6, v21, v20
	v_div_fmas_f32 v6, v6, v7, v21
	v_div_fixup_f32 v5, v6, v5, v19
	v_div_scale_f32 v6, s[4:5], v4, v4, v18
	v_rcp_f32_e32 v7, v6
	s_nop 0
	v_fma_f32 v19, -v6, v7, 1.0
	v_fmac_f32_e32 v7, v19, v7
	v_div_scale_f32 v19, vcc, v18, v4, v18
	v_mul_f32_e32 v20, v19, v7
	v_fma_f32 v21, -v6, v20, v19
	v_fmac_f32_e32 v20, v21, v7
	v_fma_f32 v6, -v6, v20, v19
	v_div_fmas_f32 v6, v6, v7, v20
	v_div_fixup_f32 v4, v6, v4, v18
	v_pk_mul_f32 v[2:3], v[2:3], v[4:5]
	v_pk_add_f32 v[6:7], v[8:9], v[36:37] op_sel_hi:[1,0] neg_lo:[0,1] neg_hi:[0,1]
	v_cvt_pk_bf16_f32 v1, v2, v3
	global_store_dwordx2 v[16:17], v[0:1], off offset:80
	s_waitcnt vmcnt(6)
	v_mov_b64_e32 v[4:5], v[166:167]
	v_mov_b64_e32 v[0:1], v[206:207]
	v_mov_b64_e32 v[2:3], v[208:209]
	v_pk_mul_f32 v[6:7], v[6:7], v[38:39] op_sel_hi:[1,0]
	v_lshlrev_b32_e32 v18, 16, v4
	v_and_b32_e32 v4, 0xffff0000, v4
	v_mul_f32_e32 v8, 0xbfb8aa3b, v18
	v_pk_mul_f32 v[0:1], v[6:7], v[0:1]
	v_mul_f32_e32 v6, 0xbfb8aa3b, v4
	v_exp_f32_e32 v8, v8
	v_exp_f32_e32 v9, v6
	s_nop 0
	v_pk_add_f32 v[6:7], v[8:9], 1.0 op_sel_hi:[1,0]
	s_nop 0
	v_div_scale_f32 v8, s[4:5], v7, v7, v4
	v_rcp_f32_e32 v9, v8
	s_nop 0
	v_fma_f32 v19, -v8, v9, 1.0
	v_fmac_f32_e32 v9, v19, v9
	v_div_scale_f32 v19, vcc, v4, v7, v4
	v_mul_f32_e32 v20, v19, v9
	v_fma_f32 v21, -v8, v20, v19
	v_fmac_f32_e32 v20, v21, v9
	v_fma_f32 v8, -v8, v20, v19
	v_div_fmas_f32 v8, v8, v9, v20
	v_div_fixup_f32 v7, v8, v7, v4
	v_div_scale_f32 v4, s[4:5], v6, v6, v18
	v_rcp_f32_e32 v8, v4
	s_nop 0
	v_fma_f32 v9, -v4, v8, 1.0
	v_fmac_f32_e32 v8, v9, v8
	v_div_scale_f32 v9, vcc, v18, v6, v18
	v_mul_f32_e32 v19, v9, v8
	v_fma_f32 v20, -v4, v19, v9
	v_fmac_f32_e32 v19, v20, v8
	v_fma_f32 v4, -v4, v19, v9
	v_div_fmas_f32 v4, v4, v8, v19
	v_lshlrev_b32_e32 v8, 16, v5
	v_and_b32_e32 v9, 0xffff0000, v5
	v_div_fixup_f32 v6, v4, v6, v18
	v_mul_f32_e32 v4, 0xbfb8aa3b, v8
	v_mul_f32_e32 v5, 0xbfb8aa3b, v9
	v_exp_f32_e32 v4, v4
	v_exp_f32_e32 v5, v5
	v_pk_mul_f32 v[0:1], v[0:1], v[6:7]
	v_pk_add_f32 v[6:7], v[10:11], v[36:37] op_sel_hi:[1,0] neg_lo:[0,1] neg_hi:[0,1]
	v_cvt_pk_bf16_f32 v0, v0, v1
	v_pk_mul_f32 v[6:7], v[6:7], v[38:39] op_sel_hi:[1,0]
	v_pk_add_f32 v[4:5], v[4:5], 1.0 op_sel_hi:[1,0]
	v_pk_mul_f32 v[2:3], v[6:7], v[2:3]
	v_div_scale_f32 v6, s[4:5], v5, v5, v9
	v_rcp_f32_e32 v7, v6
	s_nop 0
	v_fma_f32 v10, -v6, v7, 1.0
	v_fmac_f32_e32 v7, v10, v7
	v_div_scale_f32 v10, vcc, v9, v5, v9
	v_mul_f32_e32 v11, v10, v7
	v_fma_f32 v18, -v6, v11, v10
	v_fmac_f32_e32 v11, v18, v7
	v_fma_f32 v6, -v6, v11, v10
	v_div_fmas_f32 v6, v6, v7, v11
	v_div_fixup_f32 v5, v6, v5, v9
	v_div_scale_f32 v6, s[4:5], v4, v4, v8
	v_rcp_f32_e32 v7, v6
	s_nop 0
	v_fma_f32 v9, -v6, v7, 1.0
	v_fmac_f32_e32 v7, v9, v7
	v_div_scale_f32 v9, vcc, v8, v4, v8
	v_mul_f32_e32 v10, v9, v7
	v_fma_f32 v11, -v6, v10, v9
	v_fmac_f32_e32 v10, v11, v7
	v_fma_f32 v6, -v6, v10, v9
	v_div_fmas_f32 v6, v6, v7, v10
	v_div_fixup_f32 v4, v6, v4, v8
	v_pk_mul_f32 v[2:3], v[2:3], v[4:5]
	v_pk_add_f32 v[6:7], v[12:13], v[36:37] op_sel_hi:[1,0] neg_lo:[0,1] neg_hi:[0,1]
	v_cvt_pk_bf16_f32 v1, v2, v3
	global_store_dwordx2 v[16:17], v[0:1], off offset:96
	s_waitcnt vmcnt(7)
	v_mov_b64_e32 v[4:5], v[168:169]
	v_mov_b64_e32 v[0:1], v[210:211]
	v_mov_b64_e32 v[2:3], v[212:213]
	v_pk_mul_f32 v[6:7], v[6:7], v[38:39] op_sel_hi:[1,0]
	v_lshlrev_b32_e32 v10, 16, v4
	v_and_b32_e32 v4, 0xffff0000, v4
	v_mul_f32_e32 v8, 0xbfb8aa3b, v10
	v_pk_mul_f32 v[0:1], v[6:7], v[0:1]
	v_mul_f32_e32 v6, 0xbfb8aa3b, v4
	v_exp_f32_e32 v8, v8
	v_exp_f32_e32 v9, v6
	s_nop 0
	v_pk_add_f32 v[6:7], v[8:9], 1.0 op_sel_hi:[1,0]
	s_nop 0
	v_div_scale_f32 v8, s[4:5], v7, v7, v4
	v_rcp_f32_e32 v9, v8
	s_nop 0
	v_fma_f32 v11, -v8, v9, 1.0
	v_fmac_f32_e32 v9, v11, v9
	v_div_scale_f32 v11, vcc, v4, v7, v4
	v_mul_f32_e32 v12, v11, v9
	v_fma_f32 v13, -v8, v12, v11
	v_fmac_f32_e32 v12, v13, v9
	v_fma_f32 v8, -v8, v12, v11
	v_div_fmas_f32 v8, v8, v9, v12
	v_div_fixup_f32 v7, v8, v7, v4
	v_div_scale_f32 v4, s[4:5], v6, v6, v10
	v_rcp_f32_e32 v8, v4
	s_nop 0
	v_fma_f32 v9, -v4, v8, 1.0
	v_fmac_f32_e32 v8, v9, v8
	v_div_scale_f32 v9, vcc, v10, v6, v10
	v_mul_f32_e32 v11, v9, v8
	v_fma_f32 v12, -v4, v11, v9
	v_fmac_f32_e32 v11, v12, v8
	v_fma_f32 v4, -v4, v11, v9
	v_div_fmas_f32 v4, v4, v8, v11
	v_lshlrev_b32_e32 v8, 16, v5
	v_and_b32_e32 v9, 0xffff0000, v5
	v_div_fixup_f32 v6, v4, v6, v10
	v_mul_f32_e32 v4, 0xbfb8aa3b, v8
	v_mul_f32_e32 v5, 0xbfb8aa3b, v9
	v_exp_f32_e32 v4, v4
	v_exp_f32_e32 v5, v5
	v_pk_mul_f32 v[0:1], v[0:1], v[6:7]
	v_pk_add_f32 v[6:7], v[14:15], v[36:37] op_sel_hi:[1,0] neg_lo:[0,1] neg_hi:[0,1]
	v_cvt_pk_bf16_f32 v0, v0, v1
	v_pk_mul_f32 v[6:7], v[6:7], v[38:39] op_sel_hi:[1,0]
	v_pk_add_f32 v[4:5], v[4:5], 1.0 op_sel_hi:[1,0]
	v_pk_mul_f32 v[2:3], v[6:7], v[2:3]
	v_div_scale_f32 v6, s[4:5], v5, v5, v9
	v_rcp_f32_e32 v7, v6
	s_nop 0
	v_fma_f32 v10, -v6, v7, 1.0
	v_fmac_f32_e32 v7, v10, v7
	v_div_scale_f32 v10, vcc, v9, v5, v9
	v_mul_f32_e32 v11, v10, v7
	v_fma_f32 v12, -v6, v11, v10
	v_fmac_f32_e32 v11, v12, v7
	v_fma_f32 v6, -v6, v11, v10
	v_div_fmas_f32 v6, v6, v7, v11
	v_div_fixup_f32 v5, v6, v5, v9
	v_div_scale_f32 v6, s[4:5], v4, v4, v8
	v_rcp_f32_e32 v7, v6
	s_nop 0
	v_fma_f32 v9, -v6, v7, 1.0
	v_fmac_f32_e32 v7, v9, v7
	v_div_scale_f32 v9, vcc, v8, v4, v8
	v_mul_f32_e32 v10, v9, v7
	v_fma_f32 v11, -v6, v10, v9
	v_fmac_f32_e32 v10, v11, v7
	v_fma_f32 v6, -v6, v10, v9
	v_div_fmas_f32 v6, v6, v7, v10
	v_div_fixup_f32 v4, v6, v4, v8
	v_pk_mul_f32 v[2:3], v[2:3], v[4:5]
	s_nop 0
	v_cvt_pk_bf16_f32 v1, v2, v3
	global_store_dwordx2 v[16:17], v[0:1], off offset:112
	s_cbranch_scc1 .LBB0_872

.LBB0_966:
	v_add_f32_e32 v64, 0x358637bd, v65
	v_cmp_gt_f32_e32 vcc, s73, v64
	v_mul_f32_e32 v65, 0x4f800000, v64
	s_lshl_b64 s[6:7], s[36:37], 2
	v_cndmask_b32_e32 v64, v64, v65, vcc
	v_sqrt_f32_e32 v65, v64
	s_add_u32 s8, s30, s6
	s_addc_u32 s9, s31, s7
	s_lshl_b64 s[6:7], s[26:27], 2
	v_add_u32_e32 v66, -1, v65
	s_waitcnt lgkmcnt(0)
	v_fma_f32 v67, -v66, v65, v64
	v_cmp_ge_f32_e64 s[40:41], 0, v67
	v_add_u32_e32 v67, 1, v65
	s_add_u32 s22, s8, s6
	v_cndmask_b32_e64 v66, v65, v66, s[40:41]
	v_fma_f32 v65, -v67, v65, v64
	v_cmp_lt_f32_e64 s[40:41], 0, v65
	s_addc_u32 s23, s9, s7
	v_or_b32_e32 v192, s5, v138
	v_cndmask_b32_e64 v65, v66, v67, s[40:41]
	v_mul_f32_e32 v66, 0x37800000, v65
	v_cndmask_b32_e32 v65, v65, v66, vcc
	v_cmp_class_f32_e32 vcc, v64, v236
	s_lshl_b32 s42, s4, 8
	v_ashrrev_i32_e32 v125, 31, v124
	v_cndmask_b32_e32 v64, v65, v64, vcc
	v_div_scale_f32 v65, s[4:5], v64, v64, 1.0
	v_rcp_f32_e32 v66, v65
	v_ashrrev_i32_e32 v129, 31, v128
	v_lshlrev_b64 v[70:71], 1, v[124:125]
	s_ashr_i32 s43, s42, 31
	v_fma_f32 v67, -v65, v66, 1.0
	v_fmac_f32_e32 v66, v67, v66
	v_div_scale_f32 v67, vcc, 1.0, v64, 1.0
	v_mul_f32_e32 v68, v67, v66
	v_fma_f32 v69, -v65, v68, v67
	v_fmac_f32_e32 v68, v69, v66
	v_fma_f32 v65, -v65, v68, v67
	v_div_fmas_f32 v65, v65, v66, v68
	v_div_fixup_f32 v74, v65, v64, 1.0
	v_mov_b64_e32 v[64:65], s[34:35]
	v_mad_i64_i32 v[64:65], s[4:5], v128, s84, v[64:65]
	v_lshl_add_u64 v[64:65], v[192:193], 1, v[64:65]
	v_lshlrev_b64 v[66:67], 11, v[128:129]
	v_lshl_add_u64 v[76:77], v[64:65], 0, v[70:71]
	v_lshl_add_u64 v[66:67], s[20:21], 0, v[66:67]
	global_load_dwordx2 v[80:81], v[76:77], off
	v_lshl_add_u64 v[66:67], s[42:43], 1, v[66:67]
	v_lshl_add_u64 v[68:69], v[124:125], 2, s[22:23]
	v_lshl_add_u64 v[78:79], s[26:27], 1, v[66:67]
	global_load_dwordx4 v[64:67], v[68:69], off
	global_load_dwordx2 v[156:157], v[76:77], off offset:16
	global_load_dwordx2 v[158:159], v[76:77], off offset:32
	global_load_dwordx2 v[160:161], v[76:77], off offset:48
	global_load_dwordx2 v[162:163], v[76:77], off offset:64
	global_load_dwordx2 v[164:165], v[76:77], off offset:80
	global_load_dwordx2 v[166:167], v[76:77], off offset:96
	global_load_dwordx2 v[168:169], v[76:77], off offset:112
	global_load_dwordx4 v[172:175], v[68:69], off offset:32
	global_load_dwordx4 v[176:179], v[68:69], off offset:64
	global_load_dwordx4 v[180:183], v[68:69], off offset:96
	global_load_dwordx4 v[184:187], v[68:69], off offset:128
	global_load_dwordx4 v[188:191], v[68:69], off offset:160
	global_load_dwordx4 v[206:209], v[68:69], off offset:192
	global_load_dwordx4 v[210:213], v[68:69], off offset:224
	v_pk_add_f32 v[48:49], v[48:49], v[72:73] op_sel_hi:[1,0] neg_lo:[0,1] neg_hi:[0,1]
	v_pk_add_f32 v[50:51], v[50:51], v[72:73] op_sel_hi:[1,0] neg_lo:[0,1] neg_hi:[0,1]
	v_pk_add_f32 v[56:57], v[56:57], v[72:73] op_sel_hi:[1,0] neg_lo:[0,1] neg_hi:[0,1]
	v_pk_add_f32 v[32:33], v[32:33], v[72:73] op_sel_hi:[1,0] neg_lo:[0,1] neg_hi:[0,1]
	v_pk_add_f32 v[34:35], v[34:35], v[72:73] op_sel_hi:[1,0] neg_lo:[0,1] neg_hi:[0,1]
	v_pk_add_f32 v[36:37], v[36:37], v[72:73] op_sel_hi:[1,0] neg_lo:[0,1] neg_hi:[0,1]
	s_mov_b64 s[22:23], -1
	s_waitcnt vmcnt(15)
	v_lshlrev_b32_e32 v75, 16, v80
	v_and_b32_e32 v80, 0xffff0000, v80
	v_pk_mul_f32 v[48:49], v[48:49], v[74:75] op_sel_hi:[1,0]
	v_mul_f32_e32 v82, 0xbfb8aa3b, v75
	s_waitcnt vmcnt(14)
	v_pk_mul_f32 v[48:49], v[64:65], v[48:49]
	v_mul_f32_e32 v64, 0xbfb8aa3b, v80
	v_exp_f32_e32 v82, v82
	v_exp_f32_e32 v83, v64
	s_nop 0
	v_pk_add_f32 v[64:65], v[82:83], 1.0 op_sel_hi:[1,0]
	s_nop 0
	v_div_scale_f32 v82, s[4:5], v65, v65, v80
	v_rcp_f32_e32 v83, v82
	s_nop 0
	v_fma_f32 v84, -v82, v83, 1.0
	v_fmac_f32_e32 v83, v84, v83
	v_div_scale_f32 v84, vcc, v80, v65, v80
	v_mul_f32_e32 v85, v84, v83
	v_fma_f32 v86, -v82, v85, v84
	v_fmac_f32_e32 v85, v86, v83
	v_fma_f32 v82, -v82, v85, v84
	v_div_fmas_f32 v82, v82, v83, v85
	v_div_fixup_f32 v65, v82, v65, v80
	v_div_scale_f32 v80, s[4:5], v64, v64, v75
	v_rcp_f32_e32 v82, v80
	s_nop 0
	v_fma_f32 v83, -v80, v82, 1.0
	v_fmac_f32_e32 v82, v83, v82
	v_div_scale_f32 v83, vcc, v75, v64, v75
	v_mul_f32_e32 v84, v83, v82
	v_fma_f32 v85, -v80, v84, v83
	v_fmac_f32_e32 v84, v85, v82
	v_fma_f32 v80, -v80, v84, v83
	v_div_fmas_f32 v80, v80, v82, v84
	v_div_fixup_f32 v64, v80, v64, v75
	v_lshlrev_b32_e32 v75, 16, v81
	v_and_b32_e32 v80, 0xffff0000, v81
	v_pk_mul_f32 v[48:49], v[48:49], v[64:65]
	v_mul_f32_e32 v64, 0xbfb8aa3b, v75
	v_mul_f32_e32 v65, 0xbfb8aa3b, v80
	v_exp_f32_e32 v64, v64
	v_exp_f32_e32 v65, v65
	v_pk_mul_f32 v[50:51], v[50:51], v[74:75] op_sel_hi:[1,0]
	v_pk_add_f32 v[64:65], v[64:65], 1.0 op_sel_hi:[1,0]
	v_pk_mul_f32 v[50:51], v[66:67], v[50:51]
	v_div_scale_f32 v66, s[4:5], v65, v65, v80
	v_rcp_f32_e32 v67, v66
	s_nop 0
	v_fma_f32 v81, -v66, v67, 1.0
	v_fmac_f32_e32 v67, v81, v67
	v_div_scale_f32 v81, vcc, v80, v65, v80
	v_mul_f32_e32 v82, v81, v67
	v_fma_f32 v83, -v66, v82, v81
	v_fmac_f32_e32 v82, v83, v67
	v_fma_f32 v66, -v66, v82, v81
	v_div_fmas_f32 v66, v66, v67, v82
	v_div_fixup_f32 v65, v66, v65, v80
	v_div_scale_f32 v66, s[4:5], v64, v64, v75
	v_rcp_f32_e32 v67, v66
	s_nop 0
	v_fma_f32 v80, -v66, v67, 1.0
	v_fmac_f32_e32 v67, v80, v67
	v_div_scale_f32 v80, vcc, v75, v64, v75
	v_mul_f32_e32 v81, v80, v67
	v_fma_f32 v82, -v66, v81, v80
	v_fmac_f32_e32 v81, v82, v67
	v_fma_f32 v66, -v66, v81, v80
	v_div_fmas_f32 v66, v66, v67, v81
	v_div_fixup_f32 v64, v66, v64, v75
	v_pk_mul_f32 v[50:51], v[50:51], v[64:65]
	v_cvt_pk_bf16_f32 v64, v48, v49
	v_cvt_pk_bf16_f32 v65, v50, v51
	v_lshl_add_u64 v[48:49], v[78:79], 0, v[70:71]
	global_store_dwordx2 v[48:49], v[64:65], off
	s_waitcnt vmcnt(1)
	v_mov_b64_e32 v[78:79], v[156:157]
	v_mov_b64_e32 v[64:65], v[172:173]
	v_mov_b64_e32 v[66:67], v[174:175]
	v_pk_add_f32 v[50:51], v[52:53], v[72:73] op_sel_hi:[1,0] neg_lo:[0,1] neg_hi:[0,1]
	v_lshlrev_b32_e32 v75, 16, v78
	v_and_b32_e32 v78, 0xffff0000, v78
	v_mul_f32_e32 v52, 0xbfb8aa3b, v75
	v_mul_f32_e32 v53, 0xbfb8aa3b, v78
	v_exp_f32_e32 v52, v52
	v_exp_f32_e32 v53, v53
	v_pk_mul_f32 v[50:51], v[50:51], v[74:75] op_sel_hi:[1,0]
	v_pk_add_f32 v[52:53], v[52:53], 1.0 op_sel_hi:[1,0]
	v_pk_mul_f32 v[50:51], v[50:51], v[64:65]
	v_div_scale_f32 v64, s[4:5], v53, v53, v78
	v_rcp_f32_e32 v65, v64
	s_nop 0
	v_fma_f32 v80, -v64, v65, 1.0
	v_fmac_f32_e32 v65, v80, v65
	v_div_scale_f32 v80, vcc, v78, v53, v78
	v_mul_f32_e32 v81, v80, v65
	v_fma_f32 v82, -v64, v81, v80
	v_fmac_f32_e32 v81, v82, v65
	v_fma_f32 v64, -v64, v81, v80
	v_div_fmas_f32 v64, v64, v65, v81
	v_div_fixup_f32 v53, v64, v53, v78
	v_div_scale_f32 v64, s[4:5], v52, v52, v75
	v_rcp_f32_e32 v65, v64
	s_nop 0
	v_fma_f32 v78, -v64, v65, 1.0
	v_fmac_f32_e32 v65, v78, v65
	v_div_scale_f32 v78, vcc, v75, v52, v75
	v_mul_f32_e32 v80, v78, v65
	v_fma_f32 v81, -v64, v80, v78
	v_fmac_f32_e32 v80, v81, v65
	v_fma_f32 v64, -v64, v80, v78
	v_div_fmas_f32 v64, v64, v65, v80
	v_div_fixup_f32 v52, v64, v52, v75
	v_lshlrev_b32_e32 v64, 16, v79
	v_and_b32_e32 v65, 0xffff0000, v79
	v_pk_mul_f32 v[50:51], v[50:51], v[52:53]
	v_pk_add_f32 v[52:53], v[54:55], v[72:73] op_sel_hi:[1,0] neg_lo:[0,1] neg_hi:[0,1]
	v_mul_f32_e32 v54, 0xbfb8aa3b, v64
	v_mul_f32_e32 v55, 0xbfb8aa3b, v65
	v_exp_f32_e32 v54, v54
	v_exp_f32_e32 v55, v55
	v_pk_mul_f32 v[52:53], v[52:53], v[74:75] op_sel_hi:[1,0]
	v_cvt_pk_bf16_f32 v50, v50, v51
	v_pk_mul_f32 v[52:53], v[52:53], v[66:67]
	v_pk_add_f32 v[54:55], v[54:55], 1.0 op_sel_hi:[1,0]
	s_nop 0
	v_div_scale_f32 v66, s[4:5], v55, v55, v65
	v_rcp_f32_e32 v67, v66
	s_nop 0
	v_fma_f32 v75, -v66, v67, 1.0
	v_fmac_f32_e32 v67, v75, v67
	v_div_scale_f32 v75, vcc, v65, v55, v65
	v_mul_f32_e32 v78, v75, v67
	v_fma_f32 v79, -v66, v78, v75
	v_fmac_f32_e32 v78, v79, v67
	v_fma_f32 v66, -v66, v78, v75
	v_div_fmas_f32 v66, v66, v67, v78
	v_div_fixup_f32 v55, v66, v55, v65
	v_div_scale_f32 v65, s[4:5], v54, v54, v64
	v_rcp_f32_e32 v66, v65
	s_nop 0
	v_fma_f32 v67, -v65, v66, 1.0
	v_fmac_f32_e32 v66, v67, v66
	v_div_scale_f32 v67, vcc, v64, v54, v64
	v_mul_f32_e32 v75, v67, v66
	v_fma_f32 v78, -v65, v75, v67
	v_fmac_f32_e32 v75, v78, v66
	v_fma_f32 v65, -v65, v75, v67
	v_div_fmas_f32 v65, v65, v66, v75
	v_div_fixup_f32 v54, v65, v54, v64
	v_pk_mul_f32 v[52:53], v[52:53], v[54:55]
	v_pk_mul_f32 v[56:57], v[56:57], v[74:75] op_sel_hi:[1,0]
	v_cvt_pk_bf16_f32 v51, v52, v53
	global_store_dwordx2 v[48:49], v[50:51], off offset:16
	s_waitcnt vmcnt(2)
	v_mov_b64_e32 v[54:55], v[158:159]
	v_mov_b64_e32 v[50:51], v[176:177]
	v_mov_b64_e32 v[52:53], v[178:179]
	v_lshlrev_b32_e32 v66, 16, v54
	v_and_b32_e32 v54, 0xffff0000, v54
	v_mul_f32_e32 v64, 0xbfb8aa3b, v66
	v_pk_mul_f32 v[50:51], v[56:57], v[50:51]
	v_mul_f32_e32 v56, 0xbfb8aa3b, v54
	v_exp_f32_e32 v64, v64
	v_exp_f32_e32 v65, v56
	s_nop 0
	v_pk_add_f32 v[56:57], v[64:65], 1.0 op_sel_hi:[1,0]
	s_nop 0
	v_div_scale_f32 v64, s[4:5], v57, v57, v54
	v_rcp_f32_e32 v65, v64
	s_nop 0
	v_fma_f32 v67, -v64, v65, 1.0
	v_fmac_f32_e32 v65, v67, v65
	v_div_scale_f32 v67, vcc, v54, v57, v54
	v_mul_f32_e32 v75, v67, v65
	v_fma_f32 v78, -v64, v75, v67
	v_fmac_f32_e32 v75, v78, v65
	v_fma_f32 v64, -v64, v75, v67
	v_div_fmas_f32 v64, v64, v65, v75
	v_div_fixup_f32 v57, v64, v57, v54
	v_div_scale_f32 v54, s[4:5], v56, v56, v66
	v_rcp_f32_e32 v64, v54
	s_nop 0
	v_fma_f32 v65, -v54, v64, 1.0
	v_fmac_f32_e32 v64, v65, v64
	v_div_scale_f32 v65, vcc, v66, v56, v66
	v_mul_f32_e32 v67, v65, v64
	v_fma_f32 v75, -v54, v67, v65
	v_fmac_f32_e32 v67, v75, v64
	v_fma_f32 v54, -v54, v67, v65
	v_div_fmas_f32 v54, v54, v64, v67
	v_div_fixup_f32 v56, v54, v56, v66
	v_pk_mul_f32 v[50:51], v[50:51], v[56:57]
	v_pk_add_f32 v[56:57], v[58:59], v[72:73] op_sel_hi:[1,0] neg_lo:[0,1] neg_hi:[0,1]
	v_lshlrev_b32_e32 v58, 16, v55
	v_and_b32_e32 v59, 0xffff0000, v55
	v_mul_f32_e32 v54, 0xbfb8aa3b, v58
	v_mul_f32_e32 v55, 0xbfb8aa3b, v59
	v_exp_f32_e32 v54, v54
	v_exp_f32_e32 v55, v55
	v_pk_mul_f32 v[56:57], v[56:57], v[74:75] op_sel_hi:[1,0]
	v_cvt_pk_bf16_f32 v50, v50, v51
	v_pk_mul_f32 v[52:53], v[56:57], v[52:53]
	v_pk_add_f32 v[54:55], v[54:55], 1.0 op_sel_hi:[1,0]
	v_pk_mul_f32 v[32:33], v[32:33], v[74:75] op_sel_hi:[1,0]
	v_div_scale_f32 v56, s[4:5], v55, v55, v59
	v_rcp_f32_e32 v57, v56
	v_pk_mul_f32 v[34:35], v[34:35], v[74:75] op_sel_hi:[1,0]
	v_pk_mul_f32 v[36:37], v[36:37], v[74:75] op_sel_hi:[1,0]
	v_fma_f32 v64, -v56, v57, 1.0
	v_fmac_f32_e32 v57, v64, v57
	v_div_scale_f32 v64, vcc, v59, v55, v59
	v_mul_f32_e32 v65, v64, v57
	v_fma_f32 v66, -v56, v65, v64
	v_fmac_f32_e32 v65, v66, v57
	v_fma_f32 v56, -v56, v65, v64
	v_div_fmas_f32 v56, v56, v57, v65
	v_div_fixup_f32 v55, v56, v55, v59
	v_div_scale_f32 v56, s[4:5], v54, v54, v58
	v_rcp_f32_e32 v57, v56
	s_nop 0
	v_fma_f32 v59, -v56, v57, 1.0
	v_fmac_f32_e32 v57, v59, v57
	v_div_scale_f32 v59, vcc, v58, v54, v58
	v_mul_f32_e32 v64, v59, v57
	v_fma_f32 v65, -v56, v64, v59
	v_fmac_f32_e32 v64, v65, v57
	v_fma_f32 v56, -v56, v64, v59
	v_div_fmas_f32 v56, v56, v57, v64
	v_div_fixup_f32 v54, v56, v54, v58
	v_pk_mul_f32 v[52:53], v[52:53], v[54:55]
	v_pk_add_f32 v[56:57], v[60:61], v[72:73] op_sel_hi:[1,0] neg_lo:[0,1] neg_hi:[0,1]
	v_cvt_pk_bf16_f32 v51, v52, v53
	global_store_dwordx2 v[48:49], v[50:51], off offset:32
	s_waitcnt vmcnt(3)
	v_mov_b64_e32 v[54:55], v[160:161]
	v_mov_b64_e32 v[50:51], v[180:181]
	v_mov_b64_e32 v[52:53], v[182:183]
	v_pk_mul_f32 v[56:57], v[56:57], v[74:75] op_sel_hi:[1,0]
	v_lshlrev_b32_e32 v60, 16, v54
	v_and_b32_e32 v54, 0xffff0000, v54
	v_mul_f32_e32 v58, 0xbfb8aa3b, v60
	v_pk_mul_f32 v[50:51], v[56:57], v[50:51]
	v_mul_f32_e32 v56, 0xbfb8aa3b, v54
	v_exp_f32_e32 v58, v58
	v_exp_f32_e32 v59, v56
	s_nop 0
	v_pk_add_f32 v[56:57], v[58:59], 1.0 op_sel_hi:[1,0]
	s_nop 0
	v_div_scale_f32 v58, s[4:5], v57, v57, v54
	v_rcp_f32_e32 v59, v58
	s_nop 0
	v_fma_f32 v61, -v58, v59, 1.0
	v_fmac_f32_e32 v59, v61, v59
	v_div_scale_f32 v61, vcc, v54, v57, v54
	v_mul_f32_e32 v64, v61, v59
	v_fma_f32 v65, -v58, v64, v61
	v_fmac_f32_e32 v64, v65, v59
	v_fma_f32 v58, -v58, v64, v61
	v_div_fmas_f32 v58, v58, v59, v64
	v_div_fixup_f32 v57, v58, v57, v54
	v_div_scale_f32 v54, s[4:5], v56, v56, v60
	v_rcp_f32_e32 v58, v54
	s_nop 0
	v_fma_f32 v59, -v54, v58, 1.0
	v_fmac_f32_e32 v58, v59, v58
	v_div_scale_f32 v59, vcc, v60, v56, v60
	v_mul_f32_e32 v61, v59, v58
	v_fma_f32 v64, -v54, v61, v59
	v_fmac_f32_e32 v61, v64, v58
	v_fma_f32 v54, -v54, v61, v59
	v_div_fmas_f32 v54, v54, v58, v61
	v_lshlrev_b32_e32 v58, 16, v55
	v_and_b32_e32 v59, 0xffff0000, v55
	v_div_fixup_f32 v56, v54, v56, v60
	v_mul_f32_e32 v54, 0xbfb8aa3b, v58
	v_mul_f32_e32 v55, 0xbfb8aa3b, v59
	v_exp_f32_e32 v54, v54
	v_exp_f32_e32 v55, v55
	v_pk_mul_f32 v[50:51], v[50:51], v[56:57]
	v_pk_add_f32 v[56:57], v[62:63], v[72:73] op_sel_hi:[1,0] neg_lo:[0,1] neg_hi:[0,1]
	v_cvt_pk_bf16_f32 v50, v50, v51
	v_pk_mul_f32 v[56:57], v[56:57], v[74:75] op_sel_hi:[1,0]
	v_pk_add_f32 v[54:55], v[54:55], 1.0 op_sel_hi:[1,0]
	v_pk_mul_f32 v[52:53], v[56:57], v[52:53]
	v_div_scale_f32 v56, s[4:5], v55, v55, v59
	v_rcp_f32_e32 v57, v56
	s_nop 0
	v_fma_f32 v60, -v56, v57, 1.0
	v_fmac_f32_e32 v57, v60, v57
	v_div_scale_f32 v60, vcc, v59, v55, v59
	v_mul_f32_e32 v61, v60, v57
	v_fma_f32 v62, -v56, v61, v60
	v_fmac_f32_e32 v61, v62, v57
	v_fma_f32 v56, -v56, v61, v60
	v_div_fmas_f32 v56, v56, v57, v61
	v_div_fixup_f32 v55, v56, v55, v59
	v_div_scale_f32 v56, s[4:5], v54, v54, v58
	v_rcp_f32_e32 v57, v56
	s_nop 0
	v_fma_f32 v59, -v56, v57, 1.0
	v_fmac_f32_e32 v57, v59, v57
	v_div_scale_f32 v59, vcc, v58, v54, v58
	v_mul_f32_e32 v60, v59, v57
	v_fma_f32 v61, -v56, v60, v59
	v_fmac_f32_e32 v60, v61, v57
	v_fma_f32 v56, -v56, v60, v59
	v_div_fmas_f32 v56, v56, v57, v60
	v_div_fixup_f32 v54, v56, v54, v58
	v_pk_mul_f32 v[52:53], v[52:53], v[54:55]
	s_nop 0
	v_cvt_pk_bf16_f32 v51, v52, v53
	global_store_dwordx2 v[48:49], v[50:51], off offset:48
	s_waitcnt vmcnt(4)
	v_mov_b64_e32 v[54:55], v[162:163]
	v_mov_b64_e32 v[50:51], v[184:185]
	v_mov_b64_e32 v[52:53], v[186:187]
	v_lshlrev_b32_e32 v58, 16, v54
	v_and_b32_e32 v54, 0xffff0000, v54
	v_mul_f32_e32 v56, 0xbfb8aa3b, v58
	v_pk_mul_f32 v[32:33], v[32:33], v[50:51]
	v_mul_f32_e32 v50, 0xbfb8aa3b, v54
	v_exp_f32_e32 v56, v56
	v_exp_f32_e32 v57, v50
	v_pk_mul_f32 v[34:35], v[34:35], v[52:53]
	v_pk_add_f32 v[50:51], v[56:57], 1.0 op_sel_hi:[1,0]
	s_nop 0
	v_div_scale_f32 v56, s[4:5], v51, v51, v54
	v_rcp_f32_e32 v57, v56
	s_nop 0
	v_fma_f32 v59, -v56, v57, 1.0
	v_fmac_f32_e32 v57, v59, v57
	v_div_scale_f32 v59, vcc, v54, v51, v54
	v_mul_f32_e32 v60, v59, v57
	v_fma_f32 v61, -v56, v60, v59
	v_fmac_f32_e32 v60, v61, v57
	v_fma_f32 v56, -v56, v60, v59
	v_div_fmas_f32 v56, v56, v57, v60
	v_div_fixup_f32 v51, v56, v51, v54
	v_div_scale_f32 v54, s[4:5], v50, v50, v58
	v_rcp_f32_e32 v56, v54
	s_nop 0
	v_fma_f32 v57, -v54, v56, 1.0
	v_fmac_f32_e32 v56, v57, v56
	v_div_scale_f32 v57, vcc, v58, v50, v58
	v_mul_f32_e32 v59, v57, v56
	v_fma_f32 v60, -v54, v59, v57
	v_fmac_f32_e32 v59, v60, v56
	v_fma_f32 v54, -v54, v59, v57
	v_div_fmas_f32 v54, v54, v56, v59
	v_div_fixup_f32 v50, v54, v50, v58
	v_lshlrev_b32_e32 v54, 16, v55
	v_and_b32_e32 v55, 0xffff0000, v55
	v_pk_mul_f32 v[32:33], v[32:33], v[50:51]
	v_mul_f32_e32 v50, 0xbfb8aa3b, v54
	v_mul_f32_e32 v51, 0xbfb8aa3b, v55
	v_exp_f32_e32 v50, v50
	v_exp_f32_e32 v51, v51
	v_cvt_pk_bf16_f32 v32, v32, v33
	v_pk_add_f32 v[50:51], v[50:51], 1.0 op_sel_hi:[1,0]
	s_nop 0
	v_div_scale_f32 v52, s[4:5], v51, v51, v55
	v_rcp_f32_e32 v53, v52
	s_nop 0
	v_fma_f32 v56, -v52, v53, 1.0
	v_fmac_f32_e32 v53, v56, v53
	v_div_scale_f32 v56, vcc, v55, v51, v55
	v_mul_f32_e32 v57, v56, v53
	v_fma_f32 v58, -v52, v57, v56
	v_fmac_f32_e32 v57, v58, v53
	v_fma_f32 v52, -v52, v57, v56
	v_div_fmas_f32 v52, v52, v53, v57
	v_div_fixup_f32 v51, v52, v51, v55
	v_div_scale_f32 v52, s[4:5], v50, v50, v54
	v_rcp_f32_e32 v53, v52
	s_nop 0
	v_fma_f32 v55, -v52, v53, 1.0
	v_fmac_f32_e32 v53, v55, v53
	v_div_scale_f32 v55, vcc, v54, v50, v54
	v_mul_f32_e32 v56, v55, v53
	v_fma_f32 v57, -v52, v56, v55
	v_fmac_f32_e32 v56, v57, v53
	v_fma_f32 v52, -v52, v56, v55
	v_div_fmas_f32 v52, v52, v53, v56
	v_div_fixup_f32 v50, v52, v50, v54
	v_pk_mul_f32 v[34:35], v[34:35], v[50:51]
	s_nop 0
	v_cvt_pk_bf16_f32 v33, v34, v35
	global_store_dwordx2 v[48:49], v[32:33], off offset:64
	s_waitcnt vmcnt(5)
	v_mov_b64_e32 v[50:51], v[164:165]
	v_mov_b64_e32 v[32:33], v[188:189]
	v_mov_b64_e32 v[34:35], v[190:191]
	v_lshlrev_b32_e32 v54, 16, v50
	v_and_b32_e32 v50, 0xffff0000, v50
	v_mul_f32_e32 v52, 0xbfb8aa3b, v54
	v_pk_mul_f32 v[32:33], v[36:37], v[32:33]
	v_mul_f32_e32 v36, 0xbfb8aa3b, v50
	v_exp_f32_e32 v52, v52
	v_exp_f32_e32 v53, v36
	s_nop 0
	v_pk_add_f32 v[36:37], v[52:53], 1.0 op_sel_hi:[1,0]
	s_nop 0
	v_div_scale_f32 v52, s[4:5], v37, v37, v50
	v_rcp_f32_e32 v53, v52
	s_nop 0
	v_fma_f32 v55, -v52, v53, 1.0
	v_fmac_f32_e32 v53, v55, v53
	v_div_scale_f32 v55, vcc, v50, v37, v50
	v_mul_f32_e32 v56, v55, v53
	v_fma_f32 v57, -v52, v56, v55
	v_fmac_f32_e32 v56, v57, v53
	v_fma_f32 v52, -v52, v56, v55
	v_div_fmas_f32 v52, v52, v53, v56
	v_div_fixup_f32 v37, v52, v37, v50
	v_div_scale_f32 v50, s[4:5], v36, v36, v54
	v_rcp_f32_e32 v52, v50
	s_nop 0
	v_fma_f32 v53, -v50, v52, 1.0
	v_fmac_f32_e32 v52, v53, v52
	v_div_scale_f32 v53, vcc, v54, v36, v54
	v_mul_f32_e32 v55, v53, v52
	v_fma_f32 v56, -v50, v55, v53
	v_fmac_f32_e32 v55, v56, v52
	v_fma_f32 v50, -v50, v55, v53
	v_div_fmas_f32 v50, v50, v52, v55
	v_div_fixup_f32 v36, v50, v36, v54
	v_pk_mul_f32 v[32:33], v[32:33], v[36:37]
	v_pk_add_f32 v[36:37], v[38:39], v[72:73] op_sel_hi:[1,0] neg_lo:[0,1] neg_hi:[0,1]
	v_lshlrev_b32_e32 v50, 16, v51
	v_and_b32_e32 v51, 0xffff0000, v51
	v_pk_mul_f32 v[36:37], v[36:37], v[74:75] op_sel_hi:[1,0]
	v_mul_f32_e32 v38, 0xbfb8aa3b, v50
	v_pk_mul_f32 v[34:35], v[36:37], v[34:35]
	v_mul_f32_e32 v36, 0xbfb8aa3b, v51
	v_exp_f32_e32 v38, v38
	v_exp_f32_e32 v39, v36
	v_cvt_pk_bf16_f32 v32, v32, v33
	v_pk_add_f32 v[36:37], v[38:39], 1.0 op_sel_hi:[1,0]
	s_nop 0
	v_div_scale_f32 v38, s[4:5], v37, v37, v51
	v_rcp_f32_e32 v39, v38
	s_nop 0
	v_fma_f32 v52, -v38, v39, 1.0
	v_fmac_f32_e32 v39, v52, v39
	v_div_scale_f32 v52, vcc, v51, v37, v51
	v_mul_f32_e32 v53, v52, v39
	v_fma_f32 v54, -v38, v53, v52
	v_fmac_f32_e32 v53, v54, v39
	v_fma_f32 v38, -v38, v53, v52
	v_div_fmas_f32 v38, v38, v39, v53
	v_div_fixup_f32 v37, v38, v37, v51
	v_div_scale_f32 v38, s[4:5], v36, v36, v50
	v_rcp_f32_e32 v39, v38
	s_nop 0
	v_fma_f32 v51, -v38, v39, 1.0
	v_fmac_f32_e32 v39, v51, v39
	v_div_scale_f32 v51, vcc, v50, v36, v50
	v_mul_f32_e32 v52, v51, v39
	v_fma_f32 v53, -v38, v52, v51
	v_fmac_f32_e32 v52, v53, v39
	v_fma_f32 v38, -v38, v52, v51
	v_div_fmas_f32 v38, v38, v39, v52
	v_div_fixup_f32 v36, v38, v36, v50
	v_pk_mul_f32 v[34:35], v[34:35], v[36:37]
	v_pk_add_f32 v[38:39], v[40:41], v[72:73] op_sel_hi:[1,0] neg_lo:[0,1] neg_hi:[0,1]
	v_cvt_pk_bf16_f32 v33, v34, v35
	global_store_dwordx2 v[48:49], v[32:33], off offset:80
	s_waitcnt vmcnt(6)
	v_mov_b64_e32 v[36:37], v[166:167]
	v_mov_b64_e32 v[32:33], v[206:207]
	v_mov_b64_e32 v[34:35], v[208:209]
	v_pk_mul_f32 v[38:39], v[38:39], v[74:75] op_sel_hi:[1,0]
	v_lshlrev_b32_e32 v50, 16, v36
	v_and_b32_e32 v36, 0xffff0000, v36
	v_mul_f32_e32 v40, 0xbfb8aa3b, v50
	v_pk_mul_f32 v[32:33], v[38:39], v[32:33]
	v_mul_f32_e32 v38, 0xbfb8aa3b, v36
	v_exp_f32_e32 v40, v40
	v_exp_f32_e32 v41, v38
	s_nop 0
	v_pk_add_f32 v[38:39], v[40:41], 1.0 op_sel_hi:[1,0]
	s_nop 0
	v_div_scale_f32 v40, s[4:5], v39, v39, v36
	v_rcp_f32_e32 v41, v40
	s_nop 0
	v_fma_f32 v51, -v40, v41, 1.0
	v_fmac_f32_e32 v41, v51, v41
	v_div_scale_f32 v51, vcc, v36, v39, v36
	v_mul_f32_e32 v52, v51, v41
	v_fma_f32 v53, -v40, v52, v51
	v_fmac_f32_e32 v52, v53, v41
	v_fma_f32 v40, -v40, v52, v51
	v_div_fmas_f32 v40, v40, v41, v52
	v_div_fixup_f32 v39, v40, v39, v36
	v_div_scale_f32 v36, s[4:5], v38, v38, v50
	v_rcp_f32_e32 v40, v36
	s_nop 0
	v_fma_f32 v41, -v36, v40, 1.0
	v_fmac_f32_e32 v40, v41, v40
	v_div_scale_f32 v41, vcc, v50, v38, v50
	v_mul_f32_e32 v51, v41, v40
	v_fma_f32 v52, -v36, v51, v41
	v_fmac_f32_e32 v51, v52, v40
	v_fma_f32 v36, -v36, v51, v41
	v_div_fmas_f32 v36, v36, v40, v51
	v_lshlrev_b32_e32 v40, 16, v37
	v_and_b32_e32 v41, 0xffff0000, v37
	v_div_fixup_f32 v38, v36, v38, v50
	v_mul_f32_e32 v36, 0xbfb8aa3b, v40
	v_mul_f32_e32 v37, 0xbfb8aa3b, v41
	v_exp_f32_e32 v36, v36
	v_exp_f32_e32 v37, v37
	v_pk_mul_f32 v[32:33], v[32:33], v[38:39]
	v_pk_add_f32 v[38:39], v[42:43], v[72:73] op_sel_hi:[1,0] neg_lo:[0,1] neg_hi:[0,1]
	v_cvt_pk_bf16_f32 v32, v32, v33
	v_pk_mul_f32 v[38:39], v[38:39], v[74:75] op_sel_hi:[1,0]
	v_pk_add_f32 v[36:37], v[36:37], 1.0 op_sel_hi:[1,0]
	v_pk_mul_f32 v[34:35], v[38:39], v[34:35]
	v_div_scale_f32 v38, s[4:5], v37, v37, v41
	v_rcp_f32_e32 v39, v38
	s_nop 0
	v_fma_f32 v42, -v38, v39, 1.0
	v_fmac_f32_e32 v39, v42, v39
	v_div_scale_f32 v42, vcc, v41, v37, v41
	v_mul_f32_e32 v43, v42, v39
	v_fma_f32 v50, -v38, v43, v42
	v_fmac_f32_e32 v43, v50, v39
	v_fma_f32 v38, -v38, v43, v42
	v_div_fmas_f32 v38, v38, v39, v43
	v_div_fixup_f32 v37, v38, v37, v41
	v_div_scale_f32 v38, s[4:5], v36, v36, v40
	v_rcp_f32_e32 v39, v38
	s_nop 0
	v_fma_f32 v41, -v38, v39, 1.0
	v_fmac_f32_e32 v39, v41, v39
	v_div_scale_f32 v41, vcc, v40, v36, v40
	v_mul_f32_e32 v42, v41, v39
	v_fma_f32 v43, -v38, v42, v41
	v_fmac_f32_e32 v42, v43, v39
	v_fma_f32 v38, -v38, v42, v41
	v_div_fmas_f32 v38, v38, v39, v42
	v_div_fixup_f32 v36, v38, v36, v40
	v_pk_mul_f32 v[34:35], v[34:35], v[36:37]
	v_pk_add_f32 v[38:39], v[44:45], v[72:73] op_sel_hi:[1,0] neg_lo:[0,1] neg_hi:[0,1]
	v_cvt_pk_bf16_f32 v33, v34, v35
	global_store_dwordx2 v[48:49], v[32:33], off offset:96
	s_waitcnt vmcnt(7)
	v_mov_b64_e32 v[36:37], v[168:169]
	v_mov_b64_e32 v[32:33], v[210:211]
	v_mov_b64_e32 v[34:35], v[212:213]
	v_pk_mul_f32 v[38:39], v[38:39], v[74:75] op_sel_hi:[1,0]
	v_lshlrev_b32_e32 v42, 16, v36
	v_and_b32_e32 v36, 0xffff0000, v36
	v_mul_f32_e32 v40, 0xbfb8aa3b, v42
	v_pk_mul_f32 v[32:33], v[38:39], v[32:33]
	v_mul_f32_e32 v38, 0xbfb8aa3b, v36
	v_exp_f32_e32 v40, v40
	v_exp_f32_e32 v41, v38
	s_nop 0
	v_pk_add_f32 v[38:39], v[40:41], 1.0 op_sel_hi:[1,0]
	s_nop 0
	v_div_scale_f32 v40, s[4:5], v39, v39, v36
	v_rcp_f32_e32 v41, v40
	s_nop 0
	v_fma_f32 v43, -v40, v41, 1.0
	v_fmac_f32_e32 v41, v43, v41
	v_div_scale_f32 v43, vcc, v36, v39, v36
	v_mul_f32_e32 v44, v43, v41
	v_fma_f32 v45, -v40, v44, v43
	v_fmac_f32_e32 v44, v45, v41
	v_fma_f32 v40, -v40, v44, v43
	v_div_fmas_f32 v40, v40, v41, v44
	v_div_fixup_f32 v39, v40, v39, v36
	v_div_scale_f32 v36, s[4:5], v38, v38, v42
	v_rcp_f32_e32 v40, v36
	s_nop 0
	v_fma_f32 v41, -v36, v40, 1.0
	v_fmac_f32_e32 v40, v41, v40
	v_div_scale_f32 v41, vcc, v42, v38, v42
	v_mul_f32_e32 v43, v41, v40
	v_fma_f32 v44, -v36, v43, v41
	v_fmac_f32_e32 v43, v44, v40
	v_fma_f32 v36, -v36, v43, v41
	v_div_fmas_f32 v36, v36, v40, v43
	v_lshlrev_b32_e32 v40, 16, v37
	v_and_b32_e32 v41, 0xffff0000, v37
	v_div_fixup_f32 v38, v36, v38, v42
	v_mul_f32_e32 v36, 0xbfb8aa3b, v40
	v_mul_f32_e32 v37, 0xbfb8aa3b, v41
	v_exp_f32_e32 v36, v36
	v_exp_f32_e32 v37, v37
	v_pk_mul_f32 v[32:33], v[32:33], v[38:39]
	v_pk_add_f32 v[38:39], v[46:47], v[72:73] op_sel_hi:[1,0] neg_lo:[0,1] neg_hi:[0,1]
	v_cvt_pk_bf16_f32 v32, v32, v33
	v_pk_mul_f32 v[38:39], v[38:39], v[74:75] op_sel_hi:[1,0]
	v_pk_add_f32 v[36:37], v[36:37], 1.0 op_sel_hi:[1,0]
	v_pk_mul_f32 v[34:35], v[38:39], v[34:35]
	v_div_scale_f32 v38, s[4:5], v37, v37, v41
	v_rcp_f32_e32 v39, v38
	s_nop 0
	v_fma_f32 v42, -v38, v39, 1.0
	v_fmac_f32_e32 v39, v42, v39
	v_div_scale_f32 v42, vcc, v41, v37, v41
	v_mul_f32_e32 v43, v42, v39
	v_fma_f32 v44, -v38, v43, v42
	v_fmac_f32_e32 v43, v44, v39
	v_fma_f32 v38, -v38, v43, v42
	v_div_fmas_f32 v38, v38, v39, v43
	v_div_fixup_f32 v37, v38, v37, v41
	v_div_scale_f32 v38, s[4:5], v36, v36, v40
	v_rcp_f32_e32 v39, v38
	s_nop 0
	v_fma_f32 v41, -v38, v39, 1.0
	v_fmac_f32_e32 v39, v41, v39
	v_div_scale_f32 v41, vcc, v40, v36, v40
	v_mul_f32_e32 v42, v41, v39
	v_fma_f32 v43, -v38, v42, v41
	v_fmac_f32_e32 v42, v43, v39
	v_fma_f32 v38, -v38, v42, v41
	v_div_fmas_f32 v38, v38, v39, v42
	v_div_fixup_f32 v36, v38, v36, v40
	v_pk_mul_f32 v[34:35], v[34:35], v[36:37]
	s_and_b64 vcc, exec, s[38:39]
	v_cvt_pk_bf16_f32 v33, v34, v35
	v_mul_f32_e32 v35, v17, v17
	global_store_dwordx2 v[48:49], v[32:33], off offset:112
	v_add_f32_e32 v32, 0, v16
	v_fmac_f32_e32 v35, v16, v16
	v_add_f32_e32 v32, v17, v32
	v_fmac_f32_e32 v35, v18, v18
	v_add_f32_e32 v32, v18, v32
	v_fmac_f32_e32 v35, v19, v19
	v_add_f32_e32 v32, v19, v32
	v_fmac_f32_e32 v35, v20, v20
	v_add_f32_e32 v32, v20, v32
	v_fmac_f32_e32 v35, v21, v21
	v_add_f32_e32 v32, v21, v32
	v_fmac_f32_e32 v35, v22, v22
	v_add_f32_e32 v32, v22, v32
	v_fmac_f32_e32 v35, v23, v23
	v_add_f32_e32 v32, v23, v32
	v_fmac_f32_e32 v35, v24, v24
	v_add_f32_e32 v32, v24, v32
	v_fmac_f32_e32 v35, v25, v25
	v_add_f32_e32 v32, v25, v32
	v_fmac_f32_e32 v35, v26, v26
	v_add_f32_e32 v32, v26, v32
	v_fmac_f32_e32 v35, v27, v27
	v_add_f32_e32 v32, v27, v32
	v_fmac_f32_e32 v35, v28, v28
	v_add_f32_e32 v32, v28, v32
	v_fmac_f32_e32 v35, v29, v29
	v_add_f32_e32 v32, v29, v32
	v_fmac_f32_e32 v35, v30, v30
	v_add_f32_e32 v32, v30, v32
	v_fmac_f32_e32 v35, v31, v31
	v_add_f32_e32 v32, v31, v32
	v_fmac_f32_e32 v35, v0, v0
	v_add_f32_e32 v32, v0, v32
	v_fmac_f32_e32 v35, v1, v1
	v_add_f32_e32 v32, v1, v32
	v_fmac_f32_e32 v35, v2, v2
	v_add_f32_e32 v32, v2, v32
	v_fmac_f32_e32 v35, v3, v3
	v_add_f32_e32 v32, v3, v32
	v_fmac_f32_e32 v35, v4, v4
	v_add_f32_e32 v32, v4, v32
	v_fmac_f32_e32 v35, v5, v5
	v_add_f32_e32 v32, v5, v32
	v_fmac_f32_e32 v35, v6, v6
	v_add_f32_e32 v32, v6, v32
	v_fmac_f32_e32 v35, v7, v7
	v_add_f32_e32 v32, v7, v32
	v_fmac_f32_e32 v35, v8, v8
	v_add_f32_e32 v32, v8, v32
	v_fmac_f32_e32 v35, v9, v9
	v_add_f32_e32 v32, v9, v32
	v_fmac_f32_e32 v35, v10, v10
	v_add_f32_e32 v32, v10, v32
	v_fmac_f32_e32 v35, v11, v11
	v_add_f32_e32 v32, v11, v32
	v_fmac_f32_e32 v35, v12, v12
	v_add_f32_e32 v32, v12, v32
	v_fmac_f32_e32 v35, v13, v13
	v_add_f32_e32 v32, v13, v32
	v_fmac_f32_e32 v35, v14, v14
	v_add_f32_e32 v32, v14, v32
	v_fmac_f32_e32 v35, v15, v15
	v_add_f32_e32 v33, v15, v32
	ds_bpermute_b32 v32, v73, v35
	ds_bpermute_b32 v34, v73, v33
	s_waitcnt lgkmcnt(1)
	v_add_f32_e32 v32, v35, v32
	s_cbranch_vccnz .LBB0_968
	v_mul_f32_e32 v35, 0x3c800000, v32
	s_mov_b64 s[22:23], 0
